# rw_prep epilogue: loads of the k/v/a0 groups hoisted next to the first group of each j (renamed address slices, recounted vmcnt)
# speedup vs baseline: 1.1599x; 1.0064x over previous
; DEVINL float bflo(unsigned u) { return __uint_as_float(u << 16); }
; DEVINL float bfhi(unsigned u) { return __uint_as_float(u & 0xffff0000u); }
; DEVINL void rw_shift4(const char* colsb, float4 mu, unsigned o, int s, float (&out)[4]) {
;   const unsigned op = (s > 0) ? o - (unsigned)(NCP * 2) : o;
;   const unsigned on = (s < S_ - 1) ? o + (unsigned)(NCP * 2) : o;
;   const uint2 c = *(const uint2*)(colsb + o);
;   uint2 pv = *(const uint2*)(colsb + op);
;   uint2 nx = *(const uint2*)(colsb + on);
;   if (s == 0) pv = make_uint2(0u, 0u);
;   if (s == S_ - 1) nx = make_uint2(0u, 0u);
;   const float cu[4] = {bflo(c.x), bfhi(c.x), bflo(c.y), bfhi(c.y)};
;   const float pr[4] = {bflo(pv.x), bfhi(pv.x), bflo(pv.y), bfhi(pv.y)};
;   const float nn[4] = {bflo(nx.x), bfhi(nx.x), bflo(nx.y), bfhi(nx.y)};
;   const float m[4] = {mu.x, mu.y, mu.z, mu.w};
; #pragma unroll
;   for (int e = 0; e < 4; ++e) out[e] = cu[e] + m[e] * (0.5f * (pr[e] + nn[e]) - cu[e]);
; }
; DEVINL void rw_prep_unit(const Params& p, int unit) {
;     ...
;         rw_shift4(colsb, *(const float4*)(p.rw_mu + c0), rowo, s, pr);
;         rw_shift4(colsb, *(const float4*)(p.rw_mu + 1024u + c0), rowo + 2048u, s, pkr);
;         rw_shift4(colsb, *(const float4*)(p.rw_mu + 2048u + c0), rowo + 4096u, s, pv);
;         const float4 a0q = *(const float4*)(p.rw_a0 + c0), kkq = *(const float4*)(p.rw_k_k + c0);
;         const float4 kaq = *(const float4*)(p.rw_k_a + c0), rkq = *(const float4*)(p.rw_r_k + c0);
;         const float4 w0fq = *(const float4*)(p.rw_w0_f + c0), w0bq = *(const float4*)(p.rw_w0_b + c0);
.LBB0_383:
	s_nop 0
	v_mov_b32_e32 v64, s40
	v_mov_b32_e32 v65, 0
	s_cmp_eq_u32 s40, 2
	v_add_u32_e32 v96, v65, v192
	v_add_u32_e32 v194, v193, v64
	v_lshlrev_b32_e32 v178, 1, v96
	v_and_b32_e32 v212, 0xfff, v194
	v_mad_u64_u32 v[72:73], s[0:1], v194, s49, v[178:179]
	v_add_u32_e32 v68, 0x1840, v72
	v_lshlrev_b64 v[74:75], 2, v[96:97]
	v_cmp_eq_u32_e32 vcc, 0, v212
	v_add_u32_e32 v69, 0xffffc440, v72
	v_lshl_add_u64 v[64:65], s[90:91], 0, v[74:75]
	v_cndmask_b32_e32 v70, v69, v68, vcc
	v_cmp_eq_u32_e64 s[0:1], s44, v212
	v_add_u32_e32 v69, 0x6c40, v72
	global_load_dwordx4 v[64:67], v[64:65], off
	v_lshl_add_u64 v[232:233], s[72:73], 0, v[74:75]
	global_load_dwordx4 v[228:231], v[232:233], off
	v_add_u32_e32 v234, 0x2040, v72
	global_load_dwordx2 v[232:233], v234, s[18:19]
	v_add_u32_e32 v236, 0x2040, v72
	v_add_u32_e32 v237, 0xffffcc40, v72
	v_cndmask_b32_e32 v238, v237, v236, vcc
	global_load_dwordx2 v[234:235], v238, s[18:19]
	v_add_u32_e32 v238, 0x2040, v72
	v_add_u32_e32 v239, 0x7440, v72
	v_cndmask_b32_e64 v240, v239, v238, s[0:1]
	global_load_dwordx2 v[236:237], v240, s[18:19]
	v_lshl_add_u64 v[242:243], s[78:79], 0, v[74:75]
	global_load_dwordx4 v[238:241], v[242:243], off
	v_add_u32_e32 v244, 0x2840, v72
	global_load_dwordx2 v[242:243], v244, s[18:19]
	v_add_u32_e32 v246, 0x2840, v72
	v_add_u32_e32 v247, 0xffffd440, v72
	v_cndmask_b32_e32 v248, v247, v246, vcc
	global_load_dwordx2 v[244:245], v248, s[18:19]
	v_add_u32_e32 v248, 0x2840, v72
	v_add_u32_e32 v249, 0x7c40, v72
	v_cndmask_b32_e64 v250, v249, v248, s[0:1]
	global_load_dwordx2 v[246:247], v250, s[18:19]
	v_lshl_add_u64 v[252:253], s[20:21], 0, v[74:75]
	global_load_dwordx4 v[248:251], v[252:253], off
	v_cndmask_b32_e64 v73, v69, v68, s[0:1]
	global_load_dwordx2 v[68:69], v68, s[18:19]
	s_nop 0
	global_load_dwordx2 v[70:71], v70, s[18:19]
	s_nop 0
	global_load_dwordx2 v[76:77], v73, s[18:19]
	s_cselect_b64 s[6:7], -1, 0
	s_cmp_eq_u32 s40, 0
	s_cselect_b64 s[8:9], -1, 0
	v_cndmask_b32_e64 v223, v11, v10, s[6:7]
	v_cndmask_b32_e64 v223, v223, v8, s[8:9]
	s_waitcnt vmcnt(2)
	v_lshlrev_b32_e32 v209, 16, v68
	s_waitcnt vmcnt(1)
	v_cndmask_b32_e64 v70, v70, 0, vcc
	s_waitcnt vmcnt(0)
	v_cndmask_b32_e64 v73, v76, 0, s[0:1]
	v_cndmask_b32_e64 v76, v77, 0, s[0:1]
	v_and_b32_e32 v203, 0xffff0000, v68
	v_lshlrev_b32_e32 v68, 16, v70
	v_lshlrev_b32_e32 v77, 16, v73
	v_cndmask_b32_e64 v71, v71, 0, vcc
	v_lshlrev_b32_e32 v197, 16, v69
	v_and_b32_e32 v96, 0xffff0000, v69
	v_and_b32_e32 v69, 0xffff0000, v70
	v_and_b32_e32 v73, 0xffff0000, v73
	v_add_f32_e32 v68, v68, v77
	v_lshlrev_b32_e32 v70, 16, v71
	v_lshlrev_b32_e32 v78, 16, v76
	v_fma_f32 v210, v68, 0.5, -v209
	v_add_f32_e32 v68, v69, v73
	v_and_b32_e32 v71, 0xffff0000, v71
	v_and_b32_e32 v76, 0xffff0000, v76
	v_fma_f32 v204, v68, 0.5, -v203
	v_add_f32_e32 v68, v70, v78
	v_fma_f32 v198, v68, 0.5, -v197
	v_add_f32_e32 v68, v71, v76
	v_add_u32_e32 v73, 0x2040, v72
	v_add_u32_e32 v76, 0xffffcc40, v72
	v_cndmask_b32_e32 v78, v76, v73, vcc
	v_add_u32_e32 v76, 0x7440, v72
	v_fma_f32 v195, v68, 0.5, -v96
	v_lshl_add_u64 v[68:69], s[72:73], 0, v[74:75]
	v_cndmask_b32_e64 v80, v76, v73, s[0:1]
	s_nop 0
	s_nop 0
	s_nop 0
	s_nop 0
	s_nop 0
	s_nop 0
	s_nop 0
	v_fma_f32 v222, v64, v210, v209
	v_fma_f32 v221, v65, v204, v203
	v_fma_f32 v220, v66, v198, v197
	v_fma_f32 v219, v67, v195, v96
	s_waitcnt vmcnt(10)
	v_lshlrev_b32_e32 v215, 16, v232
	s_waitcnt vmcnt(9)
	v_cndmask_b32_e64 v73, v234, 0, vcc
	v_cndmask_b32_e64 v78, v235, 0, vcc
	s_waitcnt vmcnt(8)
	v_cndmask_b32_e64 v79, v236, 0, s[0:1]
	v_cndmask_b32_e64 v80, v237, 0, s[0:1]
	v_and_b32_e32 v208, 0xffff0000, v232
	v_lshlrev_b32_e32 v76, 16, v73
	v_lshlrev_b32_e32 v81, 16, v79
	v_add_f32_e32 v76, v76, v81
	v_and_b32_e32 v73, 0xffff0000, v73
	v_and_b32_e32 v79, 0xffff0000, v79
	v_fma_f32 v76, v76, 0.5, -v215
	v_fmac_f32_e32 v215, v228, v76
	v_add_f32_e32 v68, v73, v79
	v_lshlrev_b32_e32 v201, 16, v233
	v_and_b32_e32 v196, 0xffff0000, v233
	v_lshlrev_b32_e32 v77, 16, v78
	v_lshlrev_b32_e32 v82, 16, v80
	v_fma_f32 v68, v68, 0.5, -v208
	v_fmac_f32_e32 v208, v229, v68
	v_add_f32_e32 v68, v77, v82
	v_and_b32_e32 v78, 0xffff0000, v78
	v_and_b32_e32 v80, 0xffff0000, v80
	v_fma_f32 v68, v68, 0.5, -v201
	v_fmac_f32_e32 v201, v230, v68
	v_add_f32_e32 v68, v78, v80
	v_fma_f32 v68, v68, 0.5, -v196
	v_add_u32_e32 v73, 0x2840, v72
	v_add_u32_e32 v76, 0xffffd440, v72
	v_add_u32_e32 v72, 0x7c40, v72
	v_fmac_f32_e32 v196, v231, v68
	v_lshl_add_u64 v[68:69], s[78:79], 0, v[74:75]
	v_cndmask_b32_e32 v76, v76, v73, vcc
	v_cndmask_b32_e64 v78, v72, v73, s[0:1]
	s_nop 0
	s_nop 0
	s_nop 0
	s_nop 0
	s_nop 0
	s_nop 0
	s_nop 0
	s_waitcnt vmcnt(6)
	v_lshlrev_b32_e32 v216, 16, v242
	s_waitcnt vmcnt(5)
	v_cndmask_b32_e64 v76, v244, 0, vcc
	s_waitcnt vmcnt(4)
	v_cndmask_b32_e64 v78, v246, 0, s[0:1]
	v_and_b32_e32 v211, 0xffff0000, v242
	v_lshlrev_b32_e32 v72, 16, v76
	v_lshlrev_b32_e32 v80, 16, v78
	v_cndmask_b32_e64 v77, v245, 0, vcc
	v_cndmask_b32_e64 v79, v247, 0, s[0:1]
	v_lshlrev_b32_e32 v205, 16, v243
	v_and_b32_e32 v199, 0xffff0000, v243
	v_and_b32_e32 v73, 0xffff0000, v76
	v_and_b32_e32 v78, 0xffff0000, v78
	v_add_f32_e32 v72, v72, v80
	v_lshlrev_b32_e32 v76, 16, v77
	v_lshlrev_b32_e32 v81, 16, v79
	v_fma_f32 v218, v72, 0.5, -v216
	v_add_f32_e32 v72, v73, v78
	v_and_b32_e32 v77, 0xffff0000, v77
	v_and_b32_e32 v79, 0xffff0000, v79
	v_fma_f32 v214, v72, 0.5, -v211
	v_add_f32_e32 v72, v76, v81
	v_fma_f32 v207, v72, 0.5, -v205
	v_add_f32_e32 v72, v77, v79
	v_fma_f32 v202, v72, 0.5, -v199
	v_lshl_add_u64 v[72:73], s[20:21], 0, v[74:75]
	s_nop 0
	v_lshl_add_u64 v[72:73], s[26:27], 0, v[74:75]
	global_load_dwordx4 v[88:91], v[72:73], off
	v_lshl_add_u64 v[72:73], s[60:61], 0, v[74:75]
	global_load_dwordx4 v[84:87], v[72:73], off
	v_lshl_add_u64 v[72:73], s[62:63], 0, v[74:75]
	global_load_dwordx4 v[80:83], v[72:73], off
	v_lshl_add_u64 v[72:73], s[12:13], 0, v[74:75]
	global_load_dwordx4 v[76:79], v[72:73], off
	v_lshl_add_u64 v[72:73], s[16:17], 0, v[74:75]
	global_load_dwordx4 v[72:75], v[72:73], off
	v_fma_f32 v217, v238, v218, v216
	v_fma_mixlo_f16 v68, v238, v218, v216
	v_fma_f32 v213, v239, v214, v211
	v_fma_mixlo_f16 v69, v239, v214, v211
	v_fma_f32 v206, v240, v207, v205
	v_fma_mixlo_f16 v70, v240, v207, v205
	v_fma_f32 v200, v241, v202, v199
	v_fma_mixlo_f16 v71, v241, v202, v199
	s_waitcnt vmcnt(8)
; DEVINL float sigm(float x) { return 1.f / (1.f + __expf(-x)); }
; DEVINL void rw_prep_unit(const Params& p, int unit) {
;     ...
; #pragma unroll
;         for (int n = 0; n < 4; ++n) {
;           const float kraw = pkr[n];
;           float a = sigm(a0v[n] + sel4(aa[n], j));
;           av[n] = a;
;           float kk = kraw * kkp[n];
;           kkv[n] = kk;
;           n2 += kk * kk;
;           float k2 = kraw * (1.f + (a - 1.f) * kap[n]);
;           pk[n] = k2;
;           dot += pr[n] * k2 * rkp[n];
;         }
;         n2 = allred16(n2);
;         dot = allred16(dot);
;         const float inv = 1.f / fmaxf(sqrtf(n2), 1e-12f);
	v_add_f32_e32 v92, v248, v223
	v_mul_f32_e32 v92, 0xbfb8aa3b, v92
	v_exp_f32_e32 v92, v92
	s_waitcnt vmcnt(4)
	v_mul_f32_e32 v89, v208, v89
	v_mul_f32_e32 v88, v215, v88
	v_mul_f32_e32 v90, v201, v90
	v_add_f32_e32 v92, 1.0, v92
	v_div_scale_f32 v223, s[0:1], v92, v92, 1.0
	v_rcp_f32_e32 v224, v223
	v_mul_f32_e32 v91, v196, v91
	v_fma_f32 v225, -v223, v224, 1.0
	v_fmac_f32_e32 v224, v225, v224
	v_div_scale_f32 v225, vcc, 1.0, v92, 1.0
	v_mul_f32_e32 v226, v225, v224
	v_fma_f32 v227, -v223, v226, v225
	v_fmac_f32_e32 v226, v227, v224
	v_fma_f32 v223, -v223, v226, v225
	v_div_fmas_f32 v223, v223, v224, v226
	v_div_fixup_f32 v92, v223, v92, 1.0
	v_add_f32_e32 v223, -1.0, v92
	s_waitcnt vmcnt(3)
	v_fma_f32 v84, v84, v223, 1.0
	v_mul_f32_e32 v223, v215, v84
	v_mul_f32_e32 v222, v222, v223
	s_waitcnt vmcnt(2)
	v_fma_f32 v80, v80, v222, 0
	v_cndmask_b32_e64 v222, v23, v22, s[6:7]
	v_cndmask_b32_e64 v222, v222, v20, s[8:9]
	v_add_f32_e32 v93, v249, v222
	v_mul_f32_e32 v93, 0xbfb8aa3b, v93
	v_exp_f32_e32 v93, v93
	v_fma_mixlo_f16 v84, v215, v84, 0
	v_add_f32_e32 v93, 1.0, v93
	v_div_scale_f32 v222, s[0:1], v93, v93, 1.0
	v_rcp_f32_e32 v223, v222
	s_nop 0
	v_fma_f32 v224, -v222, v223, 1.0
	v_fmac_f32_e32 v223, v224, v223
	v_div_scale_f32 v224, vcc, 1.0, v93, 1.0
	v_mul_f32_e32 v225, v224, v223
	v_fma_f32 v226, -v222, v225, v224
	v_fmac_f32_e32 v225, v226, v223
	v_fma_f32 v222, -v222, v225, v224
	v_div_fmas_f32 v222, v222, v223, v225
	v_div_fixup_f32 v93, v222, v93, 1.0
	v_add_f32_e32 v223, -1.0, v93
	v_fma_f32 v85, v85, v223, 1.0
	v_mul_f32_e32 v223, v208, v85
	v_mul_f32_e32 v221, v221, v223
	v_fmac_f32_e32 v80, v81, v221
	v_cndmask_b32_e64 v81, v35, v34, s[6:7]
	v_cndmask_b32_e64 v81, v81, v32, s[8:9]
	v_add_f32_e32 v81, v250, v81
	v_mul_f32_e32 v81, 0xbfb8aa3b, v81
	v_exp_f32_e32 v81, v81
	v_mul_f32_e32 v222, v89, v89
	v_fmac_f32_e32 v222, v88, v88
	v_fmac_f32_e32 v222, v90, v90
	v_add_f32_e32 v81, 1.0, v81
	v_div_scale_f32 v94, s[0:1], v81, v81, 1.0
	v_rcp_f32_e32 v221, v94
	v_fmac_f32_e32 v222, v91, v91
	v_fma_mixlo_f16 v85, v208, v85, 0
	v_fma_f32 v223, -v94, v221, 1.0
	v_fmac_f32_e32 v221, v223, v221
	v_div_scale_f32 v223, vcc, 1.0, v81, 1.0
	v_mul_f32_e32 v224, v223, v221
	v_fma_f32 v225, -v94, v224, v223
	v_fmac_f32_e32 v224, v225, v221
	v_fma_f32 v94, -v94, v224, v223
	v_div_fmas_f32 v94, v94, v221, v224
	v_div_fixup_f32 v81, v94, v81, 1.0
	v_add_f32_e32 v94, -1.0, v81
	v_fma_f32 v86, v86, v94, 1.0
	v_mul_f32_e32 v94, v201, v86
	v_mul_f32_e32 v94, v220, v94
	v_fmac_f32_e32 v80, v82, v94
	v_cndmask_b32_e64 v82, v47, v46, s[6:7]
	v_cndmask_b32_e64 v82, v82, v44, s[8:9]
	v_add_f32_e32 v82, v251, v82
	v_mul_f32_e32 v82, 0xbfb8aa3b, v82
	v_exp_f32_e32 v82, v82
	s_nop 0
	v_add_f32_e32 v82, 1.0, v82
	v_div_scale_f32 v94, s[0:1], v82, v82, 1.0
	v_rcp_f32_e32 v95, v94
	s_nop 0
	v_fma_f32 v220, -v94, v95, 1.0
	v_fmac_f32_e32 v95, v220, v95
	v_div_scale_f32 v220, vcc, 1.0, v82, 1.0
	v_mul_f32_e32 v221, v220, v95
	v_fma_f32 v223, -v94, v221, v220
	v_fmac_f32_e32 v221, v223, v95
	v_fma_f32 v94, -v94, v221, v220
	v_div_fmas_f32 v94, v94, v95, v221
	v_div_fixup_f32 v82, v94, v82, 1.0
	v_add_f32_e32 v94, -1.0, v82
	v_fma_f32 v87, v87, v94, 1.0
	v_mul_f32_e32 v94, v196, v87
	v_mul_f32_e32 v94, v219, v94
	v_fmac_f32_e32 v80, v83, v94
	v_add_f32_dpp v83, v222, v222 quad_perm:[1,0,3,2] row_mask:0xf bank_mask:0xf bound_ctrl:1
	s_nop 0
	v_add_f32_dpp v80, v80, v80 quad_perm:[1,0,3,2] row_mask:0xf bank_mask:0xf bound_ctrl:1
	v_add_f32_dpp v83, v83, v83 quad_perm:[2,3,0,1] row_mask:0xf bank_mask:0xf bound_ctrl:1
	s_nop 0
	v_add_f32_dpp v80, v80, v80 quad_perm:[2,3,0,1] row_mask:0xf bank_mask:0xf bound_ctrl:1
	v_add_f32_dpp v83, v83, v83 row_half_mirror row_mask:0xf bank_mask:0xf bound_ctrl:1
	s_nop 0
	v_add_f32_dpp v80, v80, v80 row_half_mirror row_mask:0xf bank_mask:0xf bound_ctrl:1
	v_add_f32_dpp v83, v83, v83 row_mirror row_mask:0xf bank_mask:0xf bound_ctrl:1
	v_cmp_gt_f32_e32 vcc, s50, v83
	v_mul_f32_e32 v94, 0x4f800000, v83
	v_add_f32_dpp v80, v80, v80 row_mirror row_mask:0xf bank_mask:0xf bound_ctrl:1
	v_cndmask_b32_e32 v83, v83, v94, vcc
	v_sqrt_f32_e32 v94, v83
	s_nop 0
	v_add_u32_e32 v95, -1, v94
	v_fma_f32 v219, -v95, v94, v83
	v_cmp_ge_f32_e64 s[0:1], 0, v219
	v_add_u32_e32 v219, 1, v94
	s_nop 0
	v_cndmask_b32_e64 v95, v94, v95, s[0:1]
	v_fma_f32 v94, -v219, v94, v83
	v_cmp_lt_f32_e64 s[0:1], 0, v94
	s_nop 1
	v_cndmask_b32_e64 v94, v95, v219, s[0:1]
	v_mul_f32_e32 v95, 0x37800000, v94
	v_cndmask_b32_e32 v94, v94, v95, vcc
	v_cmp_class_f32_e32 vcc, v83, v179
	s_nop 1
	v_cndmask_b32_e32 v83, v94, v83, vcc
	v_max_f32_e32 v83, 0x2b8cbccc, v83
	v_div_scale_f32 v94, s[0:1], v83, v83, 1.0
	v_rcp_f32_e32 v95, v94
	s_nop 0
	v_fma_f32 v219, -v94, v95, 1.0
	v_fmac_f32_e32 v95, v219, v95
	v_div_scale_f32 v219, vcc, 1.0, v83, 1.0
	v_mul_f32_e32 v220, v219, v95
	v_fma_f32 v221, -v94, v220, v219
	v_fmac_f32_e32 v220, v221, v95
	v_fma_f32 v94, -v94, v220, v219
	v_div_fmas_f32 v94, v94, v95, v220
	v_lshlrev_b32_e32 v95, 10, v212
	v_cndmask_b32_e64 v212, v3, v2, s[6:7]
	v_cndmask_b32_e64 v212, v212, v0, s[8:9]
	s_waitcnt vmcnt(1)
	v_add_f32_e32 v76, v76, v212
	v_mul_f32_e32 v76, 0xbfb8aa3b, v76
	v_exp_f32_e32 v76, v76
	v_div_fixup_f32 v83, v94, v83, 1.0
	v_mul_f32_e32 v88, v88, v83
	v_lshrrev_b32_e32 v94, 8, v194
	v_add_f32_e32 v76, 1.0, v76
	v_div_scale_f32 v212, s[0:1], v76, v76, 1.0
	v_rcp_f32_e32 v219, v212
	v_and_b32_e32 v94, 0x3f0, v94
	v_fma_f32 v220, -v212, v219, 1.0
	v_fmac_f32_e32 v219, v220, v219
	v_div_scale_f32 v220, vcc, 1.0, v76, 1.0
	v_mul_f32_e32 v221, v220, v219
	v_fma_f32 v222, -v212, v221, v220
	v_fmac_f32_e32 v221, v222, v219
	v_fma_f32 v212, -v212, v221, v220
	v_div_fmas_f32 v212, v212, v219, v221
	v_div_fixup_f32 v76, v212, v76, 1.0
	v_cndmask_b32_e64 v212, v7, v6, s[6:7]
	v_cndmask_b32_e64 v212, v212, v4, s[8:9]
	s_waitcnt vmcnt(0)
; DEVINL u16 f2bf(float a) { return (u16)(pk2(a, 0.f) & 0xffffu); }
; DEVINL float sigm(float x) { return 1.f / (1.f + __expf(-x)); }
; DEVINL void rw_prep_unit(const Params& p, int unit) {
;     ...
; #pragma unroll
;         for (int n = 0; n < 4; ++n) {
;           float wf = __expf(-0.606531f * sigm(w0f[n] + sel4(awf[n], j)));
;           float wb = __expf(-0.606531f * sigm(w0b[n] + sel4(awb[n], j)));
;           float kkn = kkv[n] * inv;
;           hwf[n] = f2h(wf); hwb[n] = f2h(wb); ha[n] = f2h(-kkn); hb[n] = f2h(kkn * av[n]);
;           hk[n] = f2h(pk[n]); hr[n] = f2h(pr[n]); hv[n] = f2h(pv[n]);
;           bg[n] = f2bf(sel4(ag[n], j)); bbn[n] = f2bf(dot * pv[n]);
;         }
	v_add_f32_e32 v72, v72, v212
	v_mul_f32_e32 v72, 0xbfb8aa3b, v72
	v_exp_f32_e32 v72, v72
	v_mul_f32_e32 v76, 0xbf1b459e, v76
	v_mul_f32_e32 v76, 0x3fb8aa3b, v76
	v_exp_f32_e32 v76, v76
	v_add_f32_e32 v72, 1.0, v72
	v_div_scale_f32 v212, s[0:1], v72, v72, 1.0
	v_rcp_f32_e32 v219, v212
	v_cvt_f16_f32_e32 v76, v76
	v_fma_f32 v220, -v212, v219, 1.0
	v_fmac_f32_e32 v219, v220, v219
	v_div_scale_f32 v220, vcc, 1.0, v72, 1.0
	v_mul_f32_e32 v221, v220, v219
	v_fma_f32 v222, -v212, v221, v220
	v_fmac_f32_e32 v221, v222, v219
	v_fma_f32 v212, -v212, v221, v220
	v_div_fmas_f32 v212, v212, v219, v221
	v_div_fixup_f32 v72, v212, v72, 1.0
	v_cvt_f16_f32_e64 v212, -v88
	v_fma_mixlo_f16 v88, v92, v88, 0
	v_fma_mixlo_f16 v92, v64, v210, v209
	v_cndmask_b32_e64 v64, v51, v50, s[6:7]
	v_cndmask_b32_e64 v64, v64, v48, s[8:9]
	v_cvt_pk_bf16_f32 v209, v64, s0
	v_mul_f32_e32 v64, v217, v80
	v_cvt_pk_bf16_f32 v210, v64, s0
	v_cndmask_b32_e64 v64, v15, v14, s[6:7]
	v_cndmask_b32_e64 v64, v64, v12, s[8:9]
	v_add_f32_e32 v64, v77, v64
	v_mul_f32_e32 v64, 0xbfb8aa3b, v64
	v_exp_f32_e32 v64, v64
	v_mul_f32_e32 v72, 0xbf1b459e, v72
	v_mul_f32_e32 v72, 0x3fb8aa3b, v72
	v_exp_f32_e32 v72, v72
	v_add_f32_e32 v64, 1.0, v64
	v_div_scale_f32 v77, s[0:1], v64, v64, 1.0
	v_rcp_f32_e32 v215, v77
	v_cvt_f16_f32_e32 v72, v72
	v_fma_f32 v216, -v77, v215, 1.0
	v_fmac_f32_e32 v215, v216, v215
	v_div_scale_f32 v216, vcc, 1.0, v64, 1.0
	v_mul_f32_e32 v217, v216, v215
	v_fma_f32 v218, -v77, v217, v216
	v_fmac_f32_e32 v217, v218, v215
	v_fma_f32 v77, -v77, v217, v216
	v_div_fmas_f32 v77, v77, v215, v217
	v_div_fixup_f32 v64, v77, v64, 1.0
	v_cndmask_b32_e64 v77, v19, v18, s[6:7]
	v_cndmask_b32_e64 v77, v77, v16, s[8:9]
	v_add_f32_e32 v73, v73, v77
	v_mul_f32_e32 v73, 0xbfb8aa3b, v73
	v_exp_f32_e32 v73, v73
	v_mul_f32_e32 v64, 0xbf1b459e, v64
	v_mul_f32_e32 v64, 0x3fb8aa3b, v64
	v_exp_f32_e32 v64, v64
	v_add_f32_e32 v73, 1.0, v73
	v_div_scale_f32 v77, s[0:1], v73, v73, 1.0
	v_rcp_f32_e32 v215, v77
	v_cvt_f16_f32_sdwa v64, v64 dst_sel:WORD_1 dst_unused:UNUSED_PAD src0_sel:DWORD
	v_fma_f32 v216, -v77, v215, 1.0
	v_fmac_f32_e32 v215, v216, v215
	v_div_scale_f32 v216, vcc, 1.0, v73, 1.0
	v_mul_f32_e32 v217, v216, v215
	v_fma_f32 v218, -v77, v217, v216
	v_fmac_f32_e32 v217, v218, v215
	v_fma_f32 v77, -v77, v217, v216
	v_div_fmas_f32 v77, v77, v215, v217
	v_div_fixup_f32 v73, v77, v73, 1.0
	v_mul_f32_e32 v77, v89, v83
	v_cvt_f16_f32_sdwa v89, -v77 dst_sel:WORD_1 dst_unused:UNUSED_PAD src0_sel:DWORD
	v_fma_mixlo_f16 v77, v93, v77, 0
	v_fma_mixlo_f16 v93, v65, v204, v203
	v_cndmask_b32_e64 v65, v55, v54, s[6:7]
	v_cndmask_b32_e64 v65, v65, v52, s[8:9]
	v_cvt_pk_bf16_f32 v203, v65, s0
	v_mul_f32_e32 v65, v213, v80
	v_cvt_pk_bf16_f32 v204, v65, s0
	v_cndmask_b32_e64 v65, v27, v26, s[6:7]
	v_cndmask_b32_e64 v65, v65, v24, s[8:9]
	v_add_f32_e32 v65, v78, v65
	v_mul_f32_e32 v65, 0xbfb8aa3b, v65
	v_exp_f32_e32 v65, v65
	v_mul_f32_e32 v73, 0xbf1b459e, v73
	v_mul_f32_e32 v73, 0x3fb8aa3b, v73
	v_exp_f32_e32 v73, v73
	v_add_f32_e32 v65, 1.0, v65
	v_div_scale_f32 v78, s[0:1], v65, v65, 1.0
	v_rcp_f32_e32 v208, v78
	v_cvt_f16_f32_sdwa v73, v73 dst_sel:WORD_1 dst_unused:UNUSED_PAD src0_sel:DWORD
	v_or_b32_e32 v64, v64, v76
	v_fma_f32 v211, -v78, v208, 1.0
	v_fmac_f32_e32 v208, v211, v208
	v_div_scale_f32 v211, vcc, 1.0, v65, 1.0
	v_mul_f32_e32 v213, v211, v208
	v_fma_f32 v214, -v78, v213, v211
	v_fmac_f32_e32 v213, v214, v208
	v_fma_f32 v78, -v78, v213, v211
	v_div_fmas_f32 v78, v78, v208, v213
	v_div_fixup_f32 v65, v78, v65, 1.0
	v_cndmask_b32_e64 v78, v31, v30, s[6:7]
	v_cndmask_b32_e64 v78, v78, v28, s[8:9]
	v_add_f32_e32 v74, v74, v78
	v_mul_f32_e32 v74, 0xbfb8aa3b, v74
	v_exp_f32_e32 v74, v74
	v_mul_f32_e32 v65, 0xbf1b459e, v65
	v_mul_f32_e32 v65, 0x3fb8aa3b, v65
	v_exp_f32_e32 v65, v65
	v_add_f32_e32 v74, 1.0, v74
	v_div_scale_f32 v78, s[0:1], v74, v74, 1.0
	v_rcp_f32_e32 v208, v78
	v_cvt_f16_f32_e32 v65, v65
	v_fma_f32 v211, -v78, v208, 1.0
	v_fmac_f32_e32 v208, v211, v208
	v_div_scale_f32 v211, vcc, 1.0, v74, 1.0
	v_mul_f32_e32 v213, v211, v208
	v_fma_f32 v214, -v78, v213, v211
	v_fmac_f32_e32 v213, v214, v208
	v_fma_f32 v78, -v78, v213, v211
	v_div_fmas_f32 v78, v78, v208, v213
	v_div_fixup_f32 v74, v78, v74, 1.0
	v_mul_f32_e32 v78, v90, v83
	v_cvt_f16_f32_e64 v90, -v78
	v_fma_mixlo_f16 v78, v81, v78, 0
	v_fma_mixlo_f16 v81, v201, v86, 0
	v_fma_mixlo_f16 v86, v66, v198, v197
	v_cndmask_b32_e64 v66, v59, v58, s[6:7]
	v_cndmask_b32_e64 v66, v66, v56, s[8:9]
	v_cvt_pk_bf16_f32 v197, v66, s0
	v_mul_f32_e32 v66, v206, v80
	v_cvt_pk_bf16_f32 v198, v66, s0
	v_cndmask_b32_e64 v66, v39, v38, s[6:7]
	v_cndmask_b32_e64 v66, v66, v36, s[8:9]
	v_add_f32_e32 v66, v79, v66
	v_mul_f32_e32 v66, 0xbfb8aa3b, v66
	v_exp_f32_e32 v66, v66
	v_mul_f32_e32 v74, 0xbf1b459e, v74
	v_mul_f32_e32 v74, 0x3fb8aa3b, v74
	v_exp_f32_e32 v74, v74
	v_add_f32_e32 v66, 1.0, v66
	v_div_scale_f32 v79, s[0:1], v66, v66, 1.0
	v_rcp_f32_e32 v201, v79
	v_cvt_f16_f32_e32 v74, v74
	v_fma_f32 v205, -v79, v201, 1.0
	v_fmac_f32_e32 v201, v205, v201
	v_div_scale_f32 v205, vcc, 1.0, v66, 1.0
	v_mul_f32_e32 v206, v205, v201
	v_fma_f32 v207, -v79, v206, v205
	v_fmac_f32_e32 v206, v207, v201
	v_fma_f32 v79, -v79, v206, v205
	v_div_fmas_f32 v79, v79, v201, v206
	v_div_fixup_f32 v66, v79, v66, 1.0
	v_cndmask_b32_e64 v79, v43, v42, s[6:7]
	v_cndmask_b32_e64 v79, v79, v40, s[8:9]
	v_add_f32_e32 v75, v75, v79
	v_mul_f32_e32 v75, 0xbfb8aa3b, v75
	v_exp_f32_e32 v75, v75
	v_mul_f32_e32 v66, 0xbf1b459e, v66
	v_mul_f32_e32 v66, 0x3fb8aa3b, v66
	v_exp_f32_e32 v66, v66
	v_add_f32_e32 v75, 1.0, v75
	v_div_scale_f32 v79, s[0:1], v75, v75, 1.0
	v_rcp_f32_e32 v201, v79
; DEVINL void rw_prep_unit(const Params& p, int unit) {
;     ...
;         const int t = tok0 + mt * 16 + 4 * g + jo;
;         const int s = t & (S_ - 1), b = t >> 12;
;         const unsigned c0 = (unsigned)(head * 64 + l15 * 4 + zo);
;         const unsigned rowo = (unsigned)t * (unsigned)(NCP * 2) + (unsigned)(C_RW * 2) + c0 * 2u;
;         float pr[4], pkr[4], pv[4];
;         rw_shift4(colsb, *(const float4*)(p.rw_mu + c0), rowo, s, pr);
;         rw_shift4(colsb, *(const float4*)(p.rw_mu + 1024u + c0), rowo + 2048u, s, pkr);
;         rw_shift4(colsb, *(const float4*)(p.rw_mu + 2048u + c0), rowo + 4096u, s, pv);
;         const float4 a0q = *(const float4*)(p.rw_a0 + c0), kkq = *(const float4*)(p.rw_k_k + c0);
;     ...
;         char* rb = ws + O_REC + (reco + (unsigned)l15 * 64u);
;         *(uint4*)(rb) = make_uint4(hwf[0] | (hwf[1] << 16), hwf[2] | (hwf[3] << 16), hwb[0] | (hwb[1] << 16), hwb[2] | (hwb[3] << 16));
;         *(uint4*)(rb + 16) = make_uint4(ha[0] | (ha[1] << 16), ha[2] | (ha[3] << 16), hb[0] | (hb[1] << 16), hb[2] | (hb[3] << 16));
;         *(uint4*)(rb + 32) = make_uint4(hk[0] | (hk[1] << 16), hk[2] | (hk[3] << 16), hr[0] | (hr[1] << 16), hr[2] | (hr[3] << 16));
;         *(uint2*)(rb + 48) = make_uint2(hv[0] | (hv[1] << 16), hv[2] | (hv[3] << 16));
;         *(uint2*)(ws + O_GRW + tco) = make_uint2(bg[0] | (bg[1] << 16), bg[2] | (bg[3] << 16));
;         *(uint2*)(ws + O_BONUS + tco) = make_uint2(bbn[0] | (bbn[1] << 16), bbn[2] | (bbn[3] << 16));
	v_cvt_f16_f32_sdwa v66, v66 dst_sel:WORD_1 dst_unused:UNUSED_PAD src0_sel:DWORD
	v_fma_f32 v205, -v79, v201, 1.0
	v_fmac_f32_e32 v201, v205, v201
	v_div_scale_f32 v205, vcc, 1.0, v75, 1.0
	v_mul_f32_e32 v206, v205, v201
	v_fma_f32 v207, -v79, v206, v205
	v_fmac_f32_e32 v206, v207, v201
	v_fma_f32 v79, -v79, v206, v205
	v_div_fmas_f32 v79, v79, v201, v206
	v_div_fixup_f32 v75, v79, v75, 1.0
	v_mul_f32_e32 v75, 0xbf1b459e, v75
	v_mul_f32_e32 v75, 0x3fb8aa3b, v75
	v_exp_f32_e32 v75, v75
	v_mul_f32_e32 v79, v91, v83
	v_cvt_f16_f32_sdwa v83, -v79 dst_sel:WORD_1 dst_unused:UNUSED_PAD src0_sel:DWORD
	v_fma_mixlo_f16 v79, v82, v79, 0
	v_cvt_f16_f32_sdwa v75, v75 dst_sel:WORD_1 dst_unused:UNUSED_PAD src0_sel:DWORD
	v_fma_mixlo_f16 v82, v196, v87, 0
	v_fma_mixlo_f16 v87, v67, v195, v96
	v_cndmask_b32_e64 v67, v63, v62, s[6:7]
	v_cndmask_b32_e64 v67, v67, v60, s[8:9]
	v_cvt_pk_bf16_f32 v91, v67, s0
	v_mul_f32_e32 v67, v200, v80
	v_cvt_pk_bf16_f32 v80, v67, s0
	v_add_lshl_u32 v67, v94, v191, 22
	v_or3_b32 v95, v67, v95, v186
	v_or_b32_e32 v65, v66, v65
	v_or_b32_e32 v67, v75, v74
	v_or_b32_e32 v66, v73, v72
	global_store_dwordx4 v95, v[64:67], s[36:37]
	v_lshlrev_b32_e32 v72, 16, v77
	v_lshl_add_u32 v94, v194, 11, v178
	v_lshlrev_b32_e32 v66, 16, v79
	v_or_b32_e32 v65, v83, v90
	v_or_b32_e32 v64, v89, v212
	v_or_b32_sdwa v67, v66, v78 dst_sel:DWORD dst_unused:UNUSED_PAD src0_sel:DWORD src1_sel:WORD_0
	v_or_b32_sdwa v66, v72, v88 dst_sel:DWORD dst_unused:UNUSED_PAD src0_sel:DWORD src1_sel:WORD_0
	global_store_dwordx4 v95, v[64:67], s[36:37] offset:16
	v_lshlrev_b32_e32 v72, 16, v93
	s_add_i32 s6, s40, 1
	v_lshlrev_b32_e32 v64, 16, v82
	v_lshlrev_b32_e32 v66, 16, v85
	v_lshlrev_b32_e32 v67, 16, v87
	v_or_b32_sdwa v65, v64, v81 dst_sel:DWORD dst_unused:UNUSED_PAD src0_sel:DWORD src1_sel:WORD_0
	v_or_b32_sdwa v64, v66, v84 dst_sel:DWORD dst_unused:UNUSED_PAD src0_sel:DWORD src1_sel:WORD_0
	v_or_b32_sdwa v67, v67, v86 dst_sel:DWORD dst_unused:UNUSED_PAD src0_sel:DWORD src1_sel:WORD_0
	v_or_b32_sdwa v66, v72, v92 dst_sel:DWORD dst_unused:UNUSED_PAD src0_sel:DWORD src1_sel:WORD_0
	global_store_dwordx4 v95, v[64:67], s[36:37] offset:32
	s_cmp_eq_u32 s6, 1
	s_nop 0
	v_lshlrev_b32_e32 v64, 16, v71
	v_lshlrev_b32_e32 v66, 16, v69
	v_or_b32_sdwa v65, v64, v70 dst_sel:DWORD dst_unused:UNUSED_PAD src0_sel:DWORD src1_sel:WORD_0
	v_or_b32_sdwa v64, v66, v68 dst_sel:DWORD dst_unused:UNUSED_PAD src0_sel:DWORD src1_sel:WORD_0
	global_store_dwordx2 v95, v[64:65], s[36:37] offset:48
	v_lshlrev_b32_e32 v64, 16, v91
	v_lshlrev_b32_e32 v66, 16, v203
	v_or_b32_sdwa v65, v64, v197 dst_sel:DWORD dst_unused:UNUSED_PAD src0_sel:DWORD src1_sel:WORD_0
	v_or_b32_sdwa v64, v66, v209 dst_sel:DWORD dst_unused:UNUSED_PAD src0_sel:DWORD src1_sel:WORD_0
	global_store_dwordx2 v94, v[64:65], s[38:39]
	v_lshlrev_b32_e32 v64, 16, v80
	v_lshlrev_b32_e32 v66, 16, v204
	v_or_b32_sdwa v65, v64, v198 dst_sel:DWORD dst_unused:UNUSED_PAD src0_sel:DWORD src1_sel:WORD_0
	v_or_b32_sdwa v64, v66, v210 dst_sel:DWORD dst_unused:UNUSED_PAD src0_sel:DWORD src1_sel:WORD_0
	global_store_dwordx2 v94, v[64:65], s[70:71]
	v_mov_b32_e32 v64, s6
	v_mov_b32_e32 v65, v97
	s_cselect_b64 s[6:7], -1, 0
	v_add_u32_e32 v96, v65, v192
	v_add_u32_e32 v194, v193, v64
	v_lshlrev_b32_e32 v178, 1, v96
	v_and_b32_e32 v212, 0xfff, v194
	v_mad_u64_u32 v[72:73], s[0:1], v194, s49, v[178:179]
	v_add_u32_e32 v68, 0x1840, v72
	v_lshlrev_b64 v[74:75], 2, v[96:97]
	v_cmp_eq_u32_e32 vcc, 0, v212
	v_add_u32_e32 v69, 0xffffc440, v72
	v_lshl_add_u64 v[64:65], s[90:91], 0, v[74:75]
	v_cndmask_b32_e32 v70, v69, v68, vcc
	v_cmp_eq_u32_e64 s[0:1], s44, v212
	v_add_u32_e32 v69, 0x6c40, v72
	global_load_dwordx4 v[64:67], v[64:65], off
	v_lshl_add_u64 v[232:233], s[72:73], 0, v[74:75]
	global_load_dwordx4 v[228:231], v[232:233], off
	v_add_u32_e32 v234, 0x2040, v72
	global_load_dwordx2 v[232:233], v234, s[18:19]
	v_add_u32_e32 v236, 0x2040, v72
	v_add_u32_e32 v237, 0xffffcc40, v72
	v_cndmask_b32_e32 v238, v237, v236, vcc
	global_load_dwordx2 v[234:235], v238, s[18:19]
	v_add_u32_e32 v238, 0x2040, v72
	v_add_u32_e32 v239, 0x7440, v72
	v_cndmask_b32_e64 v240, v239, v238, s[0:1]
	global_load_dwordx2 v[236:237], v240, s[18:19]
	v_lshl_add_u64 v[242:243], s[78:79], 0, v[74:75]
	global_load_dwordx4 v[238:241], v[242:243], off
	v_add_u32_e32 v244, 0x2840, v72
	global_load_dwordx2 v[242:243], v244, s[18:19]
	v_add_u32_e32 v246, 0x2840, v72
	v_add_u32_e32 v247, 0xffffd440, v72
	v_cndmask_b32_e32 v248, v247, v246, vcc
	global_load_dwordx2 v[244:245], v248, s[18:19]
	v_add_u32_e32 v248, 0x2840, v72
	v_add_u32_e32 v249, 0x7c40, v72
	v_cndmask_b32_e64 v250, v249, v248, s[0:1]
	global_load_dwordx2 v[246:247], v250, s[18:19]
	v_lshl_add_u64 v[252:253], s[20:21], 0, v[74:75]
	global_load_dwordx4 v[248:251], v[252:253], off
	v_cndmask_b32_e64 v73, v69, v68, s[0:1]
	global_load_dwordx2 v[68:69], v68, s[18:19]
	s_nop 0
	global_load_dwordx2 v[70:71], v70, s[18:19]
	s_nop 0
	global_load_dwordx2 v[76:77], v73, s[18:19]
	v_cndmask_b32_e64 v223, v11, v9, s[6:7]
	s_add_i32 s40, s40, 2
	s_cmp_eq_u32 s40, 4
	s_waitcnt vmcnt(2)
	v_lshlrev_b32_e32 v209, 16, v68
	s_waitcnt vmcnt(1)
	v_cndmask_b32_e64 v70, v70, 0, vcc
	s_waitcnt vmcnt(0)
; DEVINL float bflo(unsigned u) { return __uint_as_float(u << 16); }
; DEVINL float bfhi(unsigned u) { return __uint_as_float(u & 0xffff0000u); }
; DEVINL void rw_shift4(const char* colsb, float4 mu, unsigned o, int s, float (&out)[4]) {
;   const unsigned op = (s > 0) ? o - (unsigned)(NCP * 2) : o;
;   const unsigned on = (s < S_ - 1) ? o + (unsigned)(NCP * 2) : o;
;   const uint2 c = *(const uint2*)(colsb + o);
;   uint2 pv = *(const uint2*)(colsb + op);
;   uint2 nx = *(const uint2*)(colsb + on);
;   if (s == 0) pv = make_uint2(0u, 0u);
;   if (s == S_ - 1) nx = make_uint2(0u, 0u);
;   const float cu[4] = {bflo(c.x), bfhi(c.x), bflo(c.y), bfhi(c.y)};
;   const float pr[4] = {bflo(pv.x), bfhi(pv.x), bflo(pv.y), bfhi(pv.y)};
;   const float nn[4] = {bflo(nx.x), bfhi(nx.x), bflo(nx.y), bfhi(nx.y)};
;   const float m[4] = {mu.x, mu.y, mu.z, mu.w};
; #pragma unroll
;   for (int e = 0; e < 4; ++e) out[e] = cu[e] + m[e] * (0.5f * (pr[e] + nn[e]) - cu[e]);
; }
; DEVINL void rw_prep_unit(const Params& p, int unit) {
;     ...
;         rw_shift4(colsb, *(const float4*)(p.rw_mu + c0), rowo, s, pr);
;         rw_shift4(colsb, *(const float4*)(p.rw_mu + 1024u + c0), rowo + 2048u, s, pkr);
;         rw_shift4(colsb, *(const float4*)(p.rw_mu + 2048u + c0), rowo + 4096u, s, pv);
;         const float4 a0q = *(const float4*)(p.rw_a0 + c0), kkq = *(const float4*)(p.rw_k_k + c0);
;         const float4 kaq = *(const float4*)(p.rw_k_a + c0), rkq = *(const float4*)(p.rw_r_k + c0);
;         const float4 w0fq = *(const float4*)(p.rw_w0_f + c0), w0bq = *(const float4*)(p.rw_w0_b + c0);
	v_cndmask_b32_e64 v73, v76, 0, s[0:1]
	v_cndmask_b32_e64 v76, v77, 0, s[0:1]
	v_and_b32_e32 v203, 0xffff0000, v68
	v_lshlrev_b32_e32 v68, 16, v70
	v_lshlrev_b32_e32 v77, 16, v73
	v_cndmask_b32_e64 v71, v71, 0, vcc
	v_lshlrev_b32_e32 v197, 16, v69
	v_and_b32_e32 v96, 0xffff0000, v69
	v_and_b32_e32 v69, 0xffff0000, v70
	v_and_b32_e32 v73, 0xffff0000, v73
	v_add_f32_e32 v68, v68, v77
	v_lshlrev_b32_e32 v70, 16, v71
	v_lshlrev_b32_e32 v78, 16, v76
	v_fma_f32 v210, v68, 0.5, -v209
	v_add_f32_e32 v68, v69, v73
	v_and_b32_e32 v71, 0xffff0000, v71
	v_and_b32_e32 v76, 0xffff0000, v76
	v_fma_f32 v204, v68, 0.5, -v203
	v_add_f32_e32 v68, v70, v78
	v_fma_f32 v198, v68, 0.5, -v197
	v_add_f32_e32 v68, v71, v76
	v_add_u32_e32 v73, 0x2040, v72
	v_add_u32_e32 v76, 0xffffcc40, v72
	v_cndmask_b32_e32 v78, v76, v73, vcc
	v_add_u32_e32 v76, 0x7440, v72
	v_fma_f32 v195, v68, 0.5, -v96
	v_lshl_add_u64 v[68:69], s[72:73], 0, v[74:75]
	v_cndmask_b32_e64 v80, v76, v73, s[0:1]
	s_nop 0
	s_nop 0
	s_nop 0
	s_nop 0
	s_nop 0
	s_nop 0
	s_nop 0
	v_fma_f32 v222, v64, v210, v209
	v_fma_f32 v221, v65, v204, v203
	v_fma_f32 v220, v66, v198, v197
	v_fma_f32 v219, v67, v195, v96
	s_waitcnt vmcnt(10)
	v_lshlrev_b32_e32 v214, 16, v232
	s_waitcnt vmcnt(9)
	v_cndmask_b32_e64 v73, v234, 0, vcc
	v_cndmask_b32_e64 v78, v235, 0, vcc
	s_waitcnt vmcnt(8)
	v_cndmask_b32_e64 v79, v236, 0, s[0:1]
	v_cndmask_b32_e64 v80, v237, 0, s[0:1]
	v_and_b32_e32 v206, 0xffff0000, v232
	v_lshlrev_b32_e32 v76, 16, v73
	v_lshlrev_b32_e32 v81, 16, v79
	v_add_f32_e32 v76, v76, v81
	v_and_b32_e32 v73, 0xffff0000, v73
	v_and_b32_e32 v79, 0xffff0000, v79
	v_fma_f32 v76, v76, 0.5, -v214
	v_fmac_f32_e32 v214, v228, v76
	v_add_f32_e32 v68, v73, v79
	v_lshlrev_b32_e32 v200, 16, v233
	v_and_b32_e32 v196, 0xffff0000, v233
	v_lshlrev_b32_e32 v77, 16, v78
	v_lshlrev_b32_e32 v82, 16, v80
	v_fma_f32 v68, v68, 0.5, -v206
	v_fmac_f32_e32 v206, v229, v68
	v_add_f32_e32 v68, v77, v82
	v_and_b32_e32 v78, 0xffff0000, v78
	v_and_b32_e32 v80, 0xffff0000, v80
	v_fma_f32 v68, v68, 0.5, -v200
	v_fmac_f32_e32 v200, v230, v68
	v_add_f32_e32 v68, v78, v80
	v_fma_f32 v68, v68, 0.5, -v196
	v_add_u32_e32 v73, 0x2840, v72
	v_add_u32_e32 v76, 0xffffd440, v72
	v_add_u32_e32 v72, 0x7c40, v72
	v_fmac_f32_e32 v196, v231, v68
	v_lshl_add_u64 v[68:69], s[78:79], 0, v[74:75]
	v_cndmask_b32_e32 v76, v76, v73, vcc
	v_cndmask_b32_e64 v78, v72, v73, s[0:1]
	s_nop 0
	s_nop 0
	s_nop 0
	s_nop 0
	s_nop 0
	s_nop 0
	s_nop 0
	s_waitcnt vmcnt(6)
	v_lshlrev_b32_e32 v216, 16, v242
	s_waitcnt vmcnt(5)
	v_cndmask_b32_e64 v76, v244, 0, vcc
	s_waitcnt vmcnt(4)
	v_cndmask_b32_e64 v78, v246, 0, s[0:1]
	v_and_b32_e32 v211, 0xffff0000, v242
	v_lshlrev_b32_e32 v72, 16, v76
	v_lshlrev_b32_e32 v80, 16, v78
	v_cndmask_b32_e64 v77, v245, 0, vcc
	v_cndmask_b32_e64 v79, v247, 0, s[0:1]
	v_lshlrev_b32_e32 v205, 16, v243
	v_and_b32_e32 v199, 0xffff0000, v243
	v_and_b32_e32 v73, 0xffff0000, v76
	v_and_b32_e32 v78, 0xffff0000, v78
	v_add_f32_e32 v72, v72, v80
	v_lshlrev_b32_e32 v76, 16, v77
	v_lshlrev_b32_e32 v81, 16, v79
	v_fma_f32 v218, v72, 0.5, -v216
	v_add_f32_e32 v72, v73, v78
	v_and_b32_e32 v77, 0xffff0000, v77
	v_and_b32_e32 v79, 0xffff0000, v79
	v_fma_f32 v215, v72, 0.5, -v211
	v_add_f32_e32 v72, v76, v81
	v_fma_f32 v208, v72, 0.5, -v205
	v_add_f32_e32 v72, v77, v79
	v_fma_f32 v202, v72, 0.5, -v199
	v_lshl_add_u64 v[72:73], s[20:21], 0, v[74:75]
	s_nop 0
	v_lshl_add_u64 v[72:73], s[26:27], 0, v[74:75]
	global_load_dwordx4 v[88:91], v[72:73], off
	v_lshl_add_u64 v[72:73], s[60:61], 0, v[74:75]
	global_load_dwordx4 v[84:87], v[72:73], off
	v_lshl_add_u64 v[72:73], s[62:63], 0, v[74:75]
	global_load_dwordx4 v[80:83], v[72:73], off
	v_lshl_add_u64 v[72:73], s[12:13], 0, v[74:75]
	global_load_dwordx4 v[76:79], v[72:73], off
	v_lshl_add_u64 v[72:73], s[16:17], 0, v[74:75]
	global_load_dwordx4 v[72:75], v[72:73], off
	v_fma_f32 v217, v238, v218, v216
	v_fma_mixlo_f16 v68, v238, v218, v216
	v_fma_f32 v213, v239, v215, v211
	v_fma_mixlo_f16 v69, v239, v215, v211
	v_fma_f32 v207, v240, v208, v205
	v_fma_mixlo_f16 v70, v240, v208, v205
	v_fma_f32 v201, v241, v202, v199
	v_fma_mixlo_f16 v71, v241, v202, v199
	s_waitcnt vmcnt(8)
	v_add_f32_e32 v92, v248, v223
	v_mul_f32_e32 v92, 0xbfb8aa3b, v92
	v_exp_f32_e32 v92, v92
	s_waitcnt vmcnt(4)
	v_mul_f32_e32 v89, v206, v89
	v_mul_f32_e32 v88, v214, v88
	v_mul_f32_e32 v90, v200, v90
	v_add_f32_e32 v92, 1.0, v92
	v_div_scale_f32 v223, s[0:1], v92, v92, 1.0
	v_rcp_f32_e32 v224, v223
	v_mul_f32_e32 v91, v196, v91
	v_fma_f32 v225, -v223, v224, 1.0
	v_fmac_f32_e32 v224, v225, v224
	v_div_scale_f32 v225, vcc, 1.0, v92, 1.0
	v_mul_f32_e32 v226, v225, v224
	v_fma_f32 v227, -v223, v226, v225
	v_fmac_f32_e32 v226, v227, v224
	v_fma_f32 v223, -v223, v226, v225
	v_div_fmas_f32 v223, v223, v224, v226
	v_div_fixup_f32 v92, v223, v92, 1.0
	v_add_f32_e32 v223, -1.0, v92
	s_waitcnt vmcnt(3)
	v_fma_f32 v84, v84, v223, 1.0
	v_mul_f32_e32 v223, v214, v84
	v_mul_f32_e32 v222, v222, v223
	s_waitcnt vmcnt(2)
; DEVINL float sigm(float x) { return 1.f / (1.f + __expf(-x)); }
; DEVINL void rw_prep_unit(const Params& p, int unit) {
;     ...
; #pragma unroll
;         for (int n = 0; n < 4; ++n) {
;           const float kraw = pkr[n];
;           float a = sigm(a0v[n] + sel4(aa[n], j));
;           av[n] = a;
;           float kk = kraw * kkp[n];
;           kkv[n] = kk;
;           n2 += kk * kk;
;           float k2 = kraw * (1.f + (a - 1.f) * kap[n]);
;           pk[n] = k2;
;           dot += pr[n] * k2 * rkp[n];
;         }
;         n2 = allred16(n2);
;         dot = allred16(dot);
;         const float inv = 1.f / fmaxf(sqrtf(n2), 1e-12f);
	v_fma_f32 v80, v80, v222, 0
	v_cndmask_b32_e64 v222, v23, v21, s[6:7]
	v_add_f32_e32 v93, v249, v222
	v_mul_f32_e32 v93, 0xbfb8aa3b, v93
	v_exp_f32_e32 v93, v93
	v_fma_mixlo_f16 v84, v214, v84, 0
	v_add_f32_e32 v93, 1.0, v93
	v_div_scale_f32 v222, s[0:1], v93, v93, 1.0
	v_rcp_f32_e32 v223, v222
	s_nop 0
	v_fma_f32 v224, -v222, v223, 1.0
	v_fmac_f32_e32 v223, v224, v223
	v_div_scale_f32 v224, vcc, 1.0, v93, 1.0
	v_mul_f32_e32 v225, v224, v223
	v_fma_f32 v226, -v222, v225, v224
	v_fmac_f32_e32 v225, v226, v223
	v_fma_f32 v222, -v222, v225, v224
	v_div_fmas_f32 v222, v222, v223, v225
	v_div_fixup_f32 v93, v222, v93, 1.0
	v_add_f32_e32 v223, -1.0, v93
	v_fma_f32 v85, v85, v223, 1.0
	v_mul_f32_e32 v223, v206, v85
	v_mul_f32_e32 v221, v221, v223
	v_fmac_f32_e32 v80, v81, v221
	v_cndmask_b32_e64 v81, v35, v33, s[6:7]
	v_add_f32_e32 v81, v250, v81
	v_mul_f32_e32 v81, 0xbfb8aa3b, v81
	v_exp_f32_e32 v81, v81
	v_mul_f32_e32 v222, v89, v89
	v_fmac_f32_e32 v222, v88, v88
	v_fmac_f32_e32 v222, v90, v90
	v_add_f32_e32 v81, 1.0, v81
	v_div_scale_f32 v94, s[0:1], v81, v81, 1.0
	v_rcp_f32_e32 v221, v94
	v_fmac_f32_e32 v222, v91, v91
	v_fma_mixlo_f16 v85, v206, v85, 0
	v_fma_f32 v223, -v94, v221, 1.0
	v_fmac_f32_e32 v221, v223, v221
	v_div_scale_f32 v223, vcc, 1.0, v81, 1.0
	v_mul_f32_e32 v224, v223, v221
	v_fma_f32 v225, -v94, v224, v223
	v_fmac_f32_e32 v224, v225, v221
	v_fma_f32 v94, -v94, v224, v223
	v_div_fmas_f32 v94, v94, v221, v224
	v_div_fixup_f32 v81, v94, v81, 1.0
	v_add_f32_e32 v94, -1.0, v81
	v_fma_f32 v86, v86, v94, 1.0
	v_mul_f32_e32 v94, v200, v86
	v_mul_f32_e32 v94, v220, v94
	v_fmac_f32_e32 v80, v82, v94
	v_cndmask_b32_e64 v82, v47, v45, s[6:7]
	v_add_f32_e32 v82, v251, v82
	v_mul_f32_e32 v82, 0xbfb8aa3b, v82
	v_exp_f32_e32 v82, v82
	s_nop 0
	v_add_f32_e32 v82, 1.0, v82
	v_div_scale_f32 v94, s[0:1], v82, v82, 1.0
	v_rcp_f32_e32 v95, v94
	s_nop 0
	v_fma_f32 v220, -v94, v95, 1.0
	v_fmac_f32_e32 v95, v220, v95
	v_div_scale_f32 v220, vcc, 1.0, v82, 1.0
	v_mul_f32_e32 v221, v220, v95
	v_fma_f32 v223, -v94, v221, v220
	v_fmac_f32_e32 v221, v223, v95
	v_fma_f32 v94, -v94, v221, v220
	v_div_fmas_f32 v94, v94, v95, v221
	v_div_fixup_f32 v82, v94, v82, 1.0
	v_add_f32_e32 v94, -1.0, v82
	v_fma_f32 v87, v87, v94, 1.0
	v_mul_f32_e32 v94, v196, v87
	v_mul_f32_e32 v94, v219, v94
	v_fmac_f32_e32 v80, v83, v94
	v_add_f32_dpp v83, v222, v222 quad_perm:[1,0,3,2] row_mask:0xf bank_mask:0xf bound_ctrl:1
	s_nop 0
	v_add_f32_dpp v80, v80, v80 quad_perm:[1,0,3,2] row_mask:0xf bank_mask:0xf bound_ctrl:1
	v_add_f32_dpp v83, v83, v83 quad_perm:[2,3,0,1] row_mask:0xf bank_mask:0xf bound_ctrl:1
	s_nop 0
	v_add_f32_dpp v80, v80, v80 quad_perm:[2,3,0,1] row_mask:0xf bank_mask:0xf bound_ctrl:1
	v_add_f32_dpp v83, v83, v83 row_half_mirror row_mask:0xf bank_mask:0xf bound_ctrl:1
	s_nop 0
	v_add_f32_dpp v80, v80, v80 row_half_mirror row_mask:0xf bank_mask:0xf bound_ctrl:1
	v_add_f32_dpp v83, v83, v83 row_mirror row_mask:0xf bank_mask:0xf bound_ctrl:1
	v_cmp_gt_f32_e32 vcc, s50, v83
	v_mul_f32_e32 v94, 0x4f800000, v83
	v_add_f32_dpp v80, v80, v80 row_mirror row_mask:0xf bank_mask:0xf bound_ctrl:1
	v_cndmask_b32_e32 v83, v83, v94, vcc
	v_sqrt_f32_e32 v94, v83
	s_nop 0
	v_add_u32_e32 v95, -1, v94
	v_fma_f32 v219, -v95, v94, v83
	v_cmp_ge_f32_e64 s[0:1], 0, v219
	v_add_u32_e32 v219, 1, v94
	s_nop 0
	v_cndmask_b32_e64 v95, v94, v95, s[0:1]
	v_fma_f32 v94, -v219, v94, v83
	v_cmp_lt_f32_e64 s[0:1], 0, v94
	s_nop 1
	v_cndmask_b32_e64 v94, v95, v219, s[0:1]
	v_mul_f32_e32 v95, 0x37800000, v94
	v_cndmask_b32_e32 v94, v94, v95, vcc
	v_cmp_class_f32_e32 vcc, v83, v179
	s_nop 1
	v_cndmask_b32_e32 v83, v94, v83, vcc
	v_max_f32_e32 v83, 0x2b8cbccc, v83
	v_div_scale_f32 v94, s[0:1], v83, v83, 1.0
	v_rcp_f32_e32 v95, v94
	s_nop 0
	v_fma_f32 v219, -v94, v95, 1.0
	v_fmac_f32_e32 v95, v219, v95
	v_div_scale_f32 v219, vcc, 1.0, v83, 1.0
	v_mul_f32_e32 v220, v219, v95
	v_fma_f32 v221, -v94, v220, v219
	v_fmac_f32_e32 v220, v221, v95
	v_fma_f32 v94, -v94, v220, v219
	v_div_fmas_f32 v94, v94, v95, v220
	v_lshlrev_b32_e32 v95, 10, v212
	v_cndmask_b32_e64 v212, v3, v1, s[6:7]
	s_waitcnt vmcnt(1)
	v_add_f32_e32 v76, v76, v212
	v_mul_f32_e32 v76, 0xbfb8aa3b, v76
	v_exp_f32_e32 v76, v76
	v_div_fixup_f32 v83, v94, v83, 1.0
	v_mul_f32_e32 v88, v88, v83
	v_lshrrev_b32_e32 v94, 8, v194
	v_add_f32_e32 v76, 1.0, v76
	v_div_scale_f32 v212, s[0:1], v76, v76, 1.0
	v_rcp_f32_e32 v219, v212
	v_and_b32_e32 v94, 0x3f0, v94
	v_fma_f32 v220, -v212, v219, 1.0
	v_fmac_f32_e32 v219, v220, v219
	v_div_scale_f32 v220, vcc, 1.0, v76, 1.0
	v_mul_f32_e32 v221, v220, v219
	v_fma_f32 v222, -v212, v221, v220
	v_fmac_f32_e32 v221, v222, v219
	v_fma_f32 v212, -v212, v221, v220
	v_div_fmas_f32 v212, v212, v219, v221
	v_div_fixup_f32 v76, v212, v76, 1.0
	v_cndmask_b32_e64 v212, v7, v5, s[6:7]
	s_waitcnt vmcnt(0)
; DEVINL u16 f2bf(float a) { return (u16)(pk2(a, 0.f) & 0xffffu); }
; DEVINL float sigm(float x) { return 1.f / (1.f + __expf(-x)); }
; DEVINL void rw_prep_unit(const Params& p, int unit) {
;     ...
; #pragma unroll
;         for (int n = 0; n < 4; ++n) {
;           float wf = __expf(-0.606531f * sigm(w0f[n] + sel4(awf[n], j)));
;           float wb = __expf(-0.606531f * sigm(w0b[n] + sel4(awb[n], j)));
;           float kkn = kkv[n] * inv;
;           hwf[n] = f2h(wf); hwb[n] = f2h(wb); ha[n] = f2h(-kkn); hb[n] = f2h(kkn * av[n]);
;           hk[n] = f2h(pk[n]); hr[n] = f2h(pr[n]); hv[n] = f2h(pv[n]);
;           bg[n] = f2bf(sel4(ag[n], j)); bbn[n] = f2bf(dot * pv[n]);
;         }
	v_add_f32_e32 v72, v72, v212
	v_mul_f32_e32 v72, 0xbfb8aa3b, v72
	v_exp_f32_e32 v72, v72
	v_mul_f32_e32 v76, 0xbf1b459e, v76
	v_mul_f32_e32 v76, 0x3fb8aa3b, v76
	v_exp_f32_e32 v76, v76
	v_add_f32_e32 v72, 1.0, v72
	v_div_scale_f32 v212, s[0:1], v72, v72, 1.0
	v_rcp_f32_e32 v219, v212
	v_cvt_f16_f32_e32 v76, v76
	v_fma_f32 v220, -v212, v219, 1.0
	v_fmac_f32_e32 v219, v220, v219
	v_div_scale_f32 v220, vcc, 1.0, v72, 1.0
	v_mul_f32_e32 v221, v220, v219
	v_fma_f32 v222, -v212, v221, v220
	v_fmac_f32_e32 v221, v222, v219
	v_fma_f32 v212, -v212, v221, v220
	v_div_fmas_f32 v212, v212, v219, v221
	v_div_fixup_f32 v72, v212, v72, 1.0
	v_cvt_f16_f32_e64 v212, -v88
	v_fma_mixlo_f16 v88, v92, v88, 0
	v_fma_mixlo_f16 v92, v64, v210, v209
	v_cndmask_b32_e64 v64, v51, v49, s[6:7]
	v_cvt_pk_bf16_f32 v209, v64, s0
	v_mul_f32_e32 v64, v217, v80
	v_cvt_pk_bf16_f32 v210, v64, s0
	v_cndmask_b32_e64 v64, v15, v13, s[6:7]
	v_add_f32_e32 v64, v77, v64
	v_mul_f32_e32 v64, 0xbfb8aa3b, v64
	v_exp_f32_e32 v64, v64
	v_mul_f32_e32 v72, 0xbf1b459e, v72
	v_mul_f32_e32 v72, 0x3fb8aa3b, v72
	v_exp_f32_e32 v72, v72
	v_add_f32_e32 v64, 1.0, v64
	v_div_scale_f32 v77, s[0:1], v64, v64, 1.0
	v_rcp_f32_e32 v214, v77
	v_cvt_f16_f32_e32 v72, v72
	v_fma_f32 v216, -v77, v214, 1.0
	v_fmac_f32_e32 v214, v216, v214
	v_div_scale_f32 v216, vcc, 1.0, v64, 1.0
	v_mul_f32_e32 v217, v216, v214
	v_fma_f32 v218, -v77, v217, v216
	v_fmac_f32_e32 v217, v218, v214
	v_fma_f32 v77, -v77, v217, v216
	v_div_fmas_f32 v77, v77, v214, v217
	v_div_fixup_f32 v64, v77, v64, 1.0
	v_cndmask_b32_e64 v77, v19, v17, s[6:7]
	v_add_f32_e32 v73, v73, v77
	v_mul_f32_e32 v73, 0xbfb8aa3b, v73
	v_exp_f32_e32 v73, v73
	v_mul_f32_e32 v64, 0xbf1b459e, v64
	v_mul_f32_e32 v64, 0x3fb8aa3b, v64
	v_exp_f32_e32 v64, v64
	v_add_f32_e32 v73, 1.0, v73
	v_div_scale_f32 v77, s[0:1], v73, v73, 1.0
	v_rcp_f32_e32 v214, v77
	v_cvt_f16_f32_sdwa v64, v64 dst_sel:WORD_1 dst_unused:UNUSED_PAD src0_sel:DWORD
	v_fma_f32 v216, -v77, v214, 1.0
	v_fmac_f32_e32 v214, v216, v214
	v_div_scale_f32 v216, vcc, 1.0, v73, 1.0
	v_mul_f32_e32 v217, v216, v214
	v_fma_f32 v218, -v77, v217, v216
	v_fmac_f32_e32 v217, v218, v214
	v_fma_f32 v77, -v77, v217, v216
	v_div_fmas_f32 v77, v77, v214, v217
	v_div_fixup_f32 v73, v77, v73, 1.0
	v_mul_f32_e32 v77, v89, v83
	v_cvt_f16_f32_sdwa v89, -v77 dst_sel:WORD_1 dst_unused:UNUSED_PAD src0_sel:DWORD
	v_fma_mixlo_f16 v77, v93, v77, 0
	v_fma_mixlo_f16 v93, v65, v204, v203
	v_cndmask_b32_e64 v65, v55, v53, s[6:7]
	v_cvt_pk_bf16_f32 v203, v65, s0
	v_mul_f32_e32 v65, v213, v80
	v_cvt_pk_bf16_f32 v204, v65, s0
	v_cndmask_b32_e64 v65, v27, v25, s[6:7]
	v_add_f32_e32 v65, v78, v65
	v_mul_f32_e32 v65, 0xbfb8aa3b, v65
	v_exp_f32_e32 v65, v65
	v_mul_f32_e32 v73, 0xbf1b459e, v73
	v_mul_f32_e32 v73, 0x3fb8aa3b, v73
	v_exp_f32_e32 v73, v73
	v_add_f32_e32 v65, 1.0, v65
	v_div_scale_f32 v78, s[0:1], v65, v65, 1.0
	v_rcp_f32_e32 v206, v78
	v_cvt_f16_f32_sdwa v73, v73 dst_sel:WORD_1 dst_unused:UNUSED_PAD src0_sel:DWORD
	v_or_b32_e32 v64, v64, v76
	v_fma_f32 v211, -v78, v206, 1.0
	v_fmac_f32_e32 v206, v211, v206
	v_div_scale_f32 v211, vcc, 1.0, v65, 1.0
	v_mul_f32_e32 v213, v211, v206
	v_fma_f32 v214, -v78, v213, v211
	v_fmac_f32_e32 v213, v214, v206
	v_fma_f32 v78, -v78, v213, v211
	v_div_fmas_f32 v78, v78, v206, v213
	v_div_fixup_f32 v65, v78, v65, 1.0
	v_cndmask_b32_e64 v78, v31, v29, s[6:7]
	v_add_f32_e32 v74, v74, v78
	v_mul_f32_e32 v74, 0xbfb8aa3b, v74
	v_exp_f32_e32 v74, v74
	v_mul_f32_e32 v65, 0xbf1b459e, v65
	v_mul_f32_e32 v65, 0x3fb8aa3b, v65
	v_exp_f32_e32 v65, v65
	v_add_f32_e32 v74, 1.0, v74
	v_div_scale_f32 v78, s[0:1], v74, v74, 1.0
	v_rcp_f32_e32 v206, v78
	v_cvt_f16_f32_e32 v65, v65
	v_fma_f32 v211, -v78, v206, 1.0
	v_fmac_f32_e32 v206, v211, v206
	v_div_scale_f32 v211, vcc, 1.0, v74, 1.0
	v_mul_f32_e32 v213, v211, v206
	v_fma_f32 v214, -v78, v213, v211
	v_fmac_f32_e32 v213, v214, v206
	v_fma_f32 v78, -v78, v213, v211
	v_div_fmas_f32 v78, v78, v206, v213
	v_div_fixup_f32 v74, v78, v74, 1.0
	v_mul_f32_e32 v78, v90, v83
	v_cvt_f16_f32_e64 v90, -v78
	v_fma_mixlo_f16 v78, v81, v78, 0
	v_fma_mixlo_f16 v81, v200, v86, 0
	v_fma_mixlo_f16 v86, v66, v198, v197
	v_cndmask_b32_e64 v66, v59, v57, s[6:7]
	v_cvt_pk_bf16_f32 v197, v66, s0
	v_mul_f32_e32 v66, v207, v80
	v_cvt_pk_bf16_f32 v198, v66, s0
; DEVINL u16 f2bf(float a) { return (u16)(pk2(a, 0.f) & 0xffffu); }
; DEVINL float sigm(float x) { return 1.f / (1.f + __expf(-x)); }
; DEVINL void rw_prep_unit(const Params& p, int unit) {
;     ...
; #pragma unroll
;         for (int n = 0; n < 4; ++n) {
;           float wf = __expf(-0.606531f * sigm(w0f[n] + sel4(awf[n], j)));
;           float wb = __expf(-0.606531f * sigm(w0b[n] + sel4(awb[n], j)));
;           float kkn = kkv[n] * inv;
;           hwf[n] = f2h(wf); hwb[n] = f2h(wb); ha[n] = f2h(-kkn); hb[n] = f2h(kkn * av[n]);
;           hk[n] = f2h(pk[n]); hr[n] = f2h(pr[n]); hv[n] = f2h(pv[n]);
;           bg[n] = f2bf(sel4(ag[n], j)); bbn[n] = f2bf(dot * pv[n]);
;         }
;         char* rb = ws + O_REC + (reco + (unsigned)l15 * 64u);
;         *(uint4*)(rb) = make_uint4(hwf[0] | (hwf[1] << 16), hwf[2] | (hwf[3] << 16), hwb[0] | (hwb[1] << 16), hwb[2] | (hwb[3] << 16));
;         *(uint4*)(rb + 16) = make_uint4(ha[0] | (ha[1] << 16), ha[2] | (ha[3] << 16), hb[0] | (hb[1] << 16), hb[2] | (hb[3] << 16));
;         *(uint4*)(rb + 32) = make_uint4(hk[0] | (hk[1] << 16), hk[2] | (hk[3] << 16), hr[0] | (hr[1] << 16), hr[2] | (hr[3] << 16));
;         *(uint2*)(rb + 48) = make_uint2(hv[0] | (hv[1] << 16), hv[2] | (hv[3] << 16));
;         *(uint2*)(ws + O_GRW + tco) = make_uint2(bg[0] | (bg[1] << 16), bg[2] | (bg[3] << 16));
;         *(uint2*)(ws + O_BONUS + tco) = make_uint2(bbn[0] | (bbn[1] << 16), bbn[2] | (bbn[3] << 16));
;       }
;     }
;   }
;   __syncthreads();
	v_cndmask_b32_e64 v66, v39, v37, s[6:7]
	v_add_f32_e32 v66, v79, v66
	v_mul_f32_e32 v66, 0xbfb8aa3b, v66
	v_exp_f32_e32 v66, v66
	v_mul_f32_e32 v74, 0xbf1b459e, v74
	v_mul_f32_e32 v74, 0x3fb8aa3b, v74
	v_exp_f32_e32 v74, v74
	v_add_f32_e32 v66, 1.0, v66
	v_div_scale_f32 v79, s[0:1], v66, v66, 1.0
	v_rcp_f32_e32 v200, v79
	v_cvt_f16_f32_e32 v74, v74
	v_fma_f32 v205, -v79, v200, 1.0
	v_fmac_f32_e32 v200, v205, v200
	v_div_scale_f32 v205, vcc, 1.0, v66, 1.0
	v_mul_f32_e32 v206, v205, v200
	v_fma_f32 v207, -v79, v206, v205
	v_fmac_f32_e32 v206, v207, v200
	v_fma_f32 v79, -v79, v206, v205
	v_div_fmas_f32 v79, v79, v200, v206
	v_div_fixup_f32 v66, v79, v66, 1.0
	v_cndmask_b32_e64 v79, v43, v41, s[6:7]
	v_add_f32_e32 v75, v75, v79
	v_mul_f32_e32 v75, 0xbfb8aa3b, v75
	v_exp_f32_e32 v75, v75
	v_mul_f32_e32 v66, 0xbf1b459e, v66
	v_mul_f32_e32 v66, 0x3fb8aa3b, v66
	v_exp_f32_e32 v66, v66
	v_add_f32_e32 v75, 1.0, v75
	v_div_scale_f32 v79, s[0:1], v75, v75, 1.0
	v_rcp_f32_e32 v200, v79
	v_cvt_f16_f32_sdwa v66, v66 dst_sel:WORD_1 dst_unused:UNUSED_PAD src0_sel:DWORD
	v_fma_f32 v205, -v79, v200, 1.0
	v_fmac_f32_e32 v200, v205, v200
	v_div_scale_f32 v205, vcc, 1.0, v75, 1.0
	v_mul_f32_e32 v206, v205, v200
	v_fma_f32 v207, -v79, v206, v205
	v_fmac_f32_e32 v206, v207, v200
	v_fma_f32 v79, -v79, v206, v205
	v_div_fmas_f32 v79, v79, v200, v206
	v_div_fixup_f32 v75, v79, v75, 1.0
	v_mul_f32_e32 v75, 0xbf1b459e, v75
	v_mul_f32_e32 v75, 0x3fb8aa3b, v75
	v_exp_f32_e32 v75, v75
	v_mul_f32_e32 v79, v91, v83
	v_cvt_f16_f32_sdwa v83, -v79 dst_sel:WORD_1 dst_unused:UNUSED_PAD src0_sel:DWORD
	v_fma_mixlo_f16 v79, v82, v79, 0
	v_cvt_f16_f32_sdwa v75, v75 dst_sel:WORD_1 dst_unused:UNUSED_PAD src0_sel:DWORD
	v_fma_mixlo_f16 v82, v196, v87, 0
	v_fma_mixlo_f16 v87, v67, v195, v96
	v_cndmask_b32_e64 v67, v63, v61, s[6:7]
	v_cvt_pk_bf16_f32 v91, v67, s0
	v_mul_f32_e32 v67, v201, v80
	v_cvt_pk_bf16_f32 v80, v67, s0
	v_add_lshl_u32 v67, v94, v191, 22
	v_or3_b32 v95, v67, v95, v186
	v_or_b32_e32 v65, v66, v65
	v_or_b32_e32 v67, v75, v74
	v_or_b32_e32 v66, v73, v72
	global_store_dwordx4 v95, v[64:67], s[36:37]
	v_lshlrev_b32_e32 v72, 16, v77
	v_lshl_add_u32 v94, v194, 11, v178
	v_lshlrev_b32_e32 v66, 16, v79
	v_or_b32_e32 v65, v83, v90
	v_or_b32_e32 v64, v89, v212
	v_or_b32_sdwa v67, v66, v78 dst_sel:DWORD dst_unused:UNUSED_PAD src0_sel:DWORD src1_sel:WORD_0
	v_or_b32_sdwa v66, v72, v88 dst_sel:DWORD dst_unused:UNUSED_PAD src0_sel:DWORD src1_sel:WORD_0
	global_store_dwordx4 v95, v[64:67], s[36:37] offset:16
	v_lshlrev_b32_e32 v72, 16, v93
	s_nop 0
	v_lshlrev_b32_e32 v64, 16, v82
	v_lshlrev_b32_e32 v66, 16, v85
	v_lshlrev_b32_e32 v67, 16, v87
	v_or_b32_sdwa v65, v64, v81 dst_sel:DWORD dst_unused:UNUSED_PAD src0_sel:DWORD src1_sel:WORD_0
	v_or_b32_sdwa v64, v66, v84 dst_sel:DWORD dst_unused:UNUSED_PAD src0_sel:DWORD src1_sel:WORD_0
	v_or_b32_sdwa v67, v67, v86 dst_sel:DWORD dst_unused:UNUSED_PAD src0_sel:DWORD src1_sel:WORD_0
	v_or_b32_sdwa v66, v72, v92 dst_sel:DWORD dst_unused:UNUSED_PAD src0_sel:DWORD src1_sel:WORD_0
	global_store_dwordx4 v95, v[64:67], s[36:37] offset:32
	s_nop 1
	v_lshlrev_b32_e32 v64, 16, v71
	v_lshlrev_b32_e32 v66, 16, v69
	v_or_b32_sdwa v65, v64, v70 dst_sel:DWORD dst_unused:UNUSED_PAD src0_sel:DWORD src1_sel:WORD_0
	v_or_b32_sdwa v64, v66, v68 dst_sel:DWORD dst_unused:UNUSED_PAD src0_sel:DWORD src1_sel:WORD_0
	global_store_dwordx2 v95, v[64:65], s[36:37] offset:48
	v_lshlrev_b32_e32 v64, 16, v91
	v_lshlrev_b32_e32 v66, 16, v203
	v_or_b32_sdwa v65, v64, v197 dst_sel:DWORD dst_unused:UNUSED_PAD src0_sel:DWORD src1_sel:WORD_0
	v_or_b32_sdwa v64, v66, v209 dst_sel:DWORD dst_unused:UNUSED_PAD src0_sel:DWORD src1_sel:WORD_0
	global_store_dwordx2 v94, v[64:65], s[38:39]
	v_lshlrev_b32_e32 v64, 16, v80
	v_lshlrev_b32_e32 v66, 16, v204
	v_or_b32_sdwa v65, v64, v198 dst_sel:DWORD dst_unused:UNUSED_PAD src0_sel:DWORD src1_sel:WORD_0
	v_or_b32_sdwa v64, v66, v210 dst_sel:DWORD dst_unused:UNUSED_PAD src0_sel:DWORD src1_sel:WORD_0
	global_store_dwordx2 v94, v[64:65], s[70:71]
	s_cbranch_scc0 .LBB0_383
	s_mov_b32 s6, 16
	s_mov_b64 s[0:1], 0
	s_and_b64 vcc, exec, s[82:83]
	s_cbranch_vccz .LBB0_382
	s_mov_b32 s6, 1
	s_and_b64 vcc, exec, s[80:81]
	s_cbranch_vccz .LBB0_381
	s_add_i32 s51, s51, s94
	s_add_i32 s3, s3, s42
	s_cmpk_lt_i32 s51, 0x100
	s_barrier
	s_cbranch_scc1 .LBB0_336
